# band loops: the 12 K and 12 V^T tiles of a workgroup's eight adjacent query tiles are brought into LDS once (cooperative LDS-DMA, two barriers per item) and read by all eight waves
# speedup vs baseline: 1.0254x; 1.0117x over previous
.Lband_entry:
	s_waitcnt vmcnt(0)
	v_lshlrev_b32_e32 v183, 2, v220
	v_add_u32_e32 v2, 0x10000, v183
	v_lshrrev_b32_e32 v183, 6, v220
	v_lshlrev_b32_e32 v183, 8, v183
	v_add_u32_e32 v183, 0x0, v183
	v_mov_b32_e32 v3, s2
	ds_write_b32 v183, v3 offset:0
	v_mov_b32_e32 v3, s3
	ds_write_b32 v183, v3 offset:4
	v_mov_b32_e32 v3, s4
	ds_write_b32 v183, v3 offset:8
	v_mov_b32_e32 v3, s5
	ds_write_b32 v183, v3 offset:12
	v_mov_b32_e32 v3, s6
	ds_write_b32 v183, v3 offset:16
	v_mov_b32_e32 v3, s7
	ds_write_b32 v183, v3 offset:20
	v_mov_b32_e32 v3, s8
	ds_write_b32 v183, v3 offset:24
	v_mov_b32_e32 v3, s9
	ds_write_b32 v183, v3 offset:28
	v_mov_b32_e32 v3, s10
	ds_write_b32 v183, v3 offset:32
	v_mov_b32_e32 v3, s11
	ds_write_b32 v183, v3 offset:36
	v_mov_b32_e32 v3, s12
	ds_write_b32 v183, v3 offset:40
	v_mov_b32_e32 v3, s13
	ds_write_b32 v183, v3 offset:44
	v_mov_b32_e32 v3, s14
	ds_write_b32 v183, v3 offset:48
	v_mov_b32_e32 v3, s15
	ds_write_b32 v183, v3 offset:52
	v_mov_b32_e32 v3, s16
	ds_write_b32 v183, v3 offset:56
	v_mov_b32_e32 v3, s17
	ds_write_b32 v183, v3 offset:60
	v_mov_b32_e32 v3, s18
	ds_write_b32 v183, v3 offset:64
	v_mov_b32_e32 v3, s19
	ds_write_b32 v183, v3 offset:68
	v_mov_b32_e32 v3, s20
	ds_write_b32 v183, v3 offset:72
	v_mov_b32_e32 v3, s21
	ds_write_b32 v183, v3 offset:76
	v_mov_b32_e32 v3, s22
	ds_write_b32 v183, v3 offset:80
	v_mov_b32_e32 v3, s23
	ds_write_b32 v183, v3 offset:84
	v_mov_b32_e32 v3, s24
	ds_write_b32 v183, v3 offset:88
	v_mov_b32_e32 v3, s25
	ds_write_b32 v183, v3 offset:92
	v_mov_b32_e32 v3, s26
	ds_write_b32 v183, v3 offset:96
	v_mov_b32_e32 v3, s27
	ds_write_b32 v183, v3 offset:100
	v_mov_b32_e32 v3, s28
	ds_write_b32 v183, v3 offset:104
	v_mov_b32_e32 v3, s29
	ds_write_b32 v183, v3 offset:108
	v_mov_b32_e32 v3, s30
	ds_write_b32 v183, v3 offset:112
	v_mov_b32_e32 v3, s34
	ds_write_b32 v183, v3 offset:116
	v_mov_b32_e32 v3, s35
	ds_write_b32 v183, v3 offset:120
	v_mov_b32_e32 v3, s36
	ds_write_b32 v183, v3 offset:124
	v_mov_b32_e32 v3, s37
	ds_write_b32 v183, v3 offset:128
	v_mov_b32_e32 v3, s38
	ds_write_b32 v183, v3 offset:132
	v_mov_b32_e32 v3, s39
	ds_write_b32 v183, v3 offset:136
	v_mov_b32_e32 v3, s40
	ds_write_b32 v183, v3 offset:140
	v_mov_b32_e32 v3, s41
	ds_write_b32 v183, v3 offset:144
	v_mov_b32_e32 v3, s42
	ds_write_b32 v183, v3 offset:148
	v_mov_b32_e32 v3, s43
	ds_write_b32 v183, v3 offset:152
	v_mov_b32_e32 v3, s44
	ds_write_b32 v183, v3 offset:156
	v_mov_b32_e32 v3, s45
	ds_write_b32 v183, v3 offset:160
	v_mov_b32_e32 v3, s46
	ds_write_b32 v183, v3 offset:164
	v_mov_b32_e32 v3, s47
	ds_write_b32 v183, v3 offset:168
	v_mov_b32_e32 v3, s48
	ds_write_b32 v183, v3 offset:172
	v_mov_b32_e32 v3, s49
	ds_write_b32 v183, v3 offset:176
	v_mov_b32_e32 v3, s50
	ds_write_b32 v183, v3 offset:180
	v_mov_b32_e32 v3, s51
	ds_write_b32 v183, v3 offset:184
	v_mov_b32_e32 v3, s52
	ds_write_b32 v183, v3 offset:188
	v_mov_b32_e32 v3, s53
	ds_write_b32 v183, v3 offset:192
	v_mov_b32_e32 v3, s54
	ds_write_b32 v183, v3 offset:196
	v_mov_b32_e32 v3, s55
	ds_write_b32 v183, v3 offset:200
	v_mov_b32_e32 v3, s56
	ds_write_b32 v183, v3 offset:204
	s_mov_b32 s52, m0
	v_mov_b32_e32 v3, s52
	ds_write_b32 v183, v3 offset:208
	v_lshrrev_b32_e32 v3, 6, v220
	s_nop 0
	v_readfirstlane_b32 s50, v3
	s_nop 3
	s_lshl_b32 s54, s50, 12
	s_add_i32 s54, s54, 0x18800
	s_load_dwordx2 s[18:19], s[70:71], 0x98
	s_load_dwordx2 s[20:21], s[70:71], 0x58
	v_and_b32_e32 v47, 31, v173
	v_lshrrev_b32_e32 v48, 5, v173
	v_lshlrev_b32_e32 v46, 4, v173
	v_mov_b32_e32 v67, 0xff800000
	v_lshlrev_b32_e32 v183, 2, v48
	v_sub_u32_e32 v54, v47, v183
	v_mov_b32_e32 v66, 0x3e38aa3b
	v_and_b32_e32 v3, 7, v47
	v_add_u32_e32 v35, 0, v48
	v_xor_b32_e32 v35, v35, v3
	v_lshlrev_b32_e32 v35, 4, v35
	v_lshl_add_u32 v35, v47, 7, v35
	v_add_u32_e32 v70, s54, v35
	v_subrev_u32_e32 v35, 0x18000, v70
	v_add_u32_e32 v36, 2, v48
	v_xor_b32_e32 v36, v36, v3
	v_lshlrev_b32_e32 v36, 4, v36
	v_lshl_add_u32 v36, v47, 7, v36
	v_add_u32_e32 v71, s54, v36
	v_subrev_u32_e32 v36, 0x18000, v71
	v_add_u32_e32 v37, 4, v48
	v_xor_b32_e32 v37, v37, v3
	v_lshlrev_b32_e32 v37, 4, v37
	v_lshl_add_u32 v37, v47, 7, v37
	v_add_u32_e32 v72, s54, v37
	v_subrev_u32_e32 v37, 0x18000, v72
	v_add_u32_e32 v38, 6, v48
	v_xor_b32_e32 v38, v38, v3
	v_lshlrev_b32_e32 v38, 4, v38
	v_lshl_add_u32 v38, v47, 7, v38
	v_add_u32_e32 v73, s54, v38
	v_subrev_u32_e32 v38, 0x18000, v73
	v_lshrrev_b32_e32 v39, 3, v173
	v_and_b32_e32 v3, 7, v173
	v_and_b32_e32 v40, 7, v39
	v_xor_b32_e32 v40, v3, v40
	v_lshlrev_b32_e32 v40, 4, v40
	v_add_u32_e32 v74, s54, v46
	v_subrev_u32_e32 v74, 0xc000, v74
	s_mov_b32 s0, s1
	s_waitcnt lgkmcnt(0)

.Lband_dec_done:
	s_mul_i32 s17, s23, 0x1600000
	s_add_u32 s2, s18, s17
	s_addc_u32 s3, s19, 0
	s_add_u32 s2, s2, 0x5600000
	s_addc_u32 s3, s3, 0
	s_lshl_b32 s11, 0x2c000, s9
	v_lshl_add_u32 v183, s8, 5, v47
	v_lshlrev_b32_e32 v183, s9, v183
	v_add_u32_e32 v57, s10, v183
	v_lshlrev_b32_e32 v183, s9, v39
	v_add_u32_e32 v183, s10, v183
	v_mul_u32_u24_e32 v41, 0x1600, v183
	v_add_u32_e32 v41, s12, v41
	v_add_u32_e32 v41, v41, v40
	s_lshl_b32 s51, 0xb000, s9
	s_sub_i32 s53, s8, s50
	s_barrier
	s_mul_i32 s17, s8, s11
	s_sub_i32 s16, s13, s12
	s_add_i32 s17, s17, s16
	v_add_u32_e32 v42, s17, v41
	v_add_u32_e32 v43, s51, v42
	v_add_u32_e32 v44, s51, v43
	v_add_u32_e32 v45, s51, v44
	s_add_i32 m0, s54, 0x0
	global_load_lds_dwordx4 v42, s[2:3]
	s_add_i32 m0, s54, 0x400
	global_load_lds_dwordx4 v43, s[2:3]
	s_add_i32 m0, s54, 0x800
	global_load_lds_dwordx4 v44, s[2:3]
	s_add_i32 m0, s54, 0xc00
	global_load_lds_dwordx4 v45, s[2:3]
	s_mul_i32 s16, s50, 3
	s_add_i32 s16, s16, 0
	s_cmp_lt_u32 s16, 12
	s_cbranch_scc0 .Lband_ldv0
	s_lshl_b32 s55, s16, 12
	s_add_i32 s55, s55, 0x800
	s_add_i32 s16, s16, s53
	s_add_i32 s16, s16, -4
	s_max_i32 s16, s16, 0
	s_mul_i32 s17, s16, s11
	v_add_u32_e32 v42, s17, v41
	v_add_u32_e32 v43, s51, v42
	v_add_u32_e32 v44, s51, v43
	v_add_u32_e32 v45, s51, v44
	s_add_i32 m0, s55, 0x0
	global_load_lds_dwordx4 v42, s[2:3]
	s_add_i32 m0, s55, 0x400
	global_load_lds_dwordx4 v43, s[2:3]
	s_add_i32 m0, s55, 0x800
	global_load_lds_dwordx4 v44, s[2:3]
	s_add_i32 m0, s55, 0xc00
	global_load_lds_dwordx4 v45, s[2:3]
	s_branch .Lband_ldd0
.Lband_ldv0:
	s_add_i32 s16, s16, -12
	s_lshl_b32 s55, s16, 12
	s_add_i32 s55, s55, 0xc800
	s_add_i32 s16, s16, s53
	s_add_i32 s16, s16, -4
	s_max_i32 s16, s16, 0
	s_lshl_b32 s17, s16, 12
	v_add_u32_e32 v42, s17, v46
	v_add_u32_e32 v43, 0x400, v42
	v_add_u32_e32 v44, 0x400, v43
	v_add_u32_e32 v45, 0x400, v44
	s_add_i32 m0, s55, 0x0
	global_load_lds_dwordx4 v42, s[4:5]
	s_add_i32 m0, s55, 0x400
	global_load_lds_dwordx4 v43, s[4:5]
	s_add_i32 m0, s55, 0x800
	global_load_lds_dwordx4 v44, s[4:5]
	s_add_i32 m0, s55, 0xc00
	global_load_lds_dwordx4 v45, s[4:5]
.Lband_ldd0:
	s_mul_i32 s16, s50, 3
	s_add_i32 s16, s16, 1
	s_cmp_lt_u32 s16, 12
	s_cbranch_scc0 .Lband_ldv1
	s_lshl_b32 s55, s16, 12
	s_add_i32 s55, s55, 0x800
	s_add_i32 s16, s16, s53
	s_add_i32 s16, s16, -4
	s_max_i32 s16, s16, 0
	s_mul_i32 s17, s16, s11
	v_add_u32_e32 v42, s17, v41
	v_add_u32_e32 v43, s51, v42
	v_add_u32_e32 v44, s51, v43
	v_add_u32_e32 v45, s51, v44
	s_add_i32 m0, s55, 0x0
	global_load_lds_dwordx4 v42, s[2:3]
	s_add_i32 m0, s55, 0x400
	global_load_lds_dwordx4 v43, s[2:3]
	s_add_i32 m0, s55, 0x800
	global_load_lds_dwordx4 v44, s[2:3]
	s_add_i32 m0, s55, 0xc00
	global_load_lds_dwordx4 v45, s[2:3]
	s_branch .Lband_ldd1

.Lband_ldd1:
	s_mul_i32 s16, s50, 3
	s_add_i32 s16, s16, 2
	s_cmp_lt_u32 s16, 12
	s_cbranch_scc0 .Lband_ldv2
	s_lshl_b32 s55, s16, 12
	s_add_i32 s55, s55, 0x800
	s_add_i32 s16, s16, s53
	s_add_i32 s16, s16, -4
	s_max_i32 s16, s16, 0
	s_mul_i32 s17, s16, s11
	v_add_u32_e32 v42, s17, v41
	v_add_u32_e32 v43, s51, v42
	v_add_u32_e32 v44, s51, v43
	v_add_u32_e32 v45, s51, v44
	s_add_i32 m0, s55, 0x0
	global_load_lds_dwordx4 v42, s[2:3]
	s_add_i32 m0, s55, 0x400
	global_load_lds_dwordx4 v43, s[2:3]
	s_add_i32 m0, s55, 0x800
	global_load_lds_dwordx4 v44, s[2:3]
	s_add_i32 m0, s55, 0xc00
	global_load_lds_dwordx4 v45, s[2:3]
	s_branch .Lband_ldd2

.Lband_ldd2:
	v_cvt_f32_i32_e32 v51, s24
	v_mul_f32_e32 v51, 0xbf2aaaab, v51
	v_exp_f32_e32 v51, v51
	v_cvt_f32_i32_e32 v52, v54
	v_mul_f32_e32 v51, 0x3fb8aa3b, v51
	v_ldexp_f32 v51, v51, s9
	v_mul_f32_e64 v52, -v51, v52
	v_mul_f32_e32 v18, 0x00000000, v51
	v_mul_f32_e32 v19, 0x3f800000, v51
	v_mul_f32_e32 v20, 0x40000000, v51
	v_mul_f32_e32 v21, 0x40400000, v51
	v_mul_f32_e32 v22, 0x41000000, v51
	v_mul_f32_e32 v23, 0x41100000, v51
	v_mul_f32_e32 v24, 0x41200000, v51
	v_mul_f32_e32 v25, 0x41300000, v51
	v_mul_f32_e32 v26, 0x41800000, v51
	v_mul_f32_e32 v27, 0x41880000, v51
	v_mul_f32_e32 v28, 0x41900000, v51
	v_mul_f32_e32 v29, 0x41980000, v51
	v_mul_f32_e32 v30, 0x41c00000, v51
	v_mul_f32_e32 v31, 0x41c80000, v51
	v_mul_f32_e32 v32, 0x41d00000, v51
	v_mul_f32_e32 v33, 0x41d80000, v51
	v_readfirstlane_b32 s34, v18
	v_readfirstlane_b32 s35, v19
	v_readfirstlane_b32 s36, v20
	v_readfirstlane_b32 s37, v21
	v_readfirstlane_b32 s38, v22
	v_readfirstlane_b32 s39, v23
	v_readfirstlane_b32 s40, v24
	v_readfirstlane_b32 s41, v25
	v_readfirstlane_b32 s42, v26
	v_readfirstlane_b32 s43, v27
	v_readfirstlane_b32 s44, v28
	v_readfirstlane_b32 s45, v29
	v_readfirstlane_b32 s46, v30
	v_readfirstlane_b32 s47, v31
	v_readfirstlane_b32 s48, v32
	v_readfirstlane_b32 s49, v33
	v_add_u32_e32 v55, s15, v54
	v_lshlrev_b32_e32 v62, s14, v57
	v_lshl_add_u32 v62, v48, 3, v62
	v_lshlrev_b32_e32 v63, 4, v57
	v_mov_b32_e32 v49, 0xf149f2ca
	v_mov_b32_e32 v34, 0xf149f2ca
	v_mov_b32_e32 v50, 0
	v_mov_b32_e32 v146, 0
	v_mov_b32_e32 v147, 0
	v_mov_b32_e32 v148, 0
	v_mov_b32_e32 v149, 0
	v_mov_b32_e32 v150, 0
	v_mov_b32_e32 v151, 0
	v_mov_b32_e32 v152, 0
	v_mov_b32_e32 v153, 0
	v_mov_b32_e32 v154, 0
	v_mov_b32_e32 v155, 0
	v_mov_b32_e32 v156, 0
	v_mov_b32_e32 v157, 0
	v_mov_b32_e32 v158, 0
	v_mov_b32_e32 v159, 0
	v_mov_b32_e32 v160, 0
	v_mov_b32_e32 v161, 0
	v_mov_b32_e32 v184, 0
	v_mov_b32_e32 v185, 0
	v_mov_b32_e32 v186, 0
	v_mov_b32_e32 v187, 0
	v_mov_b32_e32 v188, 0
	v_mov_b32_e32 v189, 0
	v_mov_b32_e32 v190, 0
	v_mov_b32_e32 v191, 0
	v_mov_b32_e32 v192, 0
	v_mov_b32_e32 v193, 0
	v_mov_b32_e32 v194, 0
	v_mov_b32_e32 v195, 0
	v_mov_b32_e32 v196, 0
	v_mov_b32_e32 v197, 0
	v_mov_b32_e32 v198, 0
	v_mov_b32_e32 v199, 0
	s_waitcnt vmcnt(0)
	s_barrier
	ds_read_b128 v[130:133], v70
	ds_read_b128 v[134:137], v71
	ds_read_b128 v[138:141], v72
	ds_read_b128 v[142:145], v73
	s_waitcnt lgkmcnt(0)
	s_cmp_lt_i32 s8, 4
	s_cbranch_scc1 .Lband_s0a
	ds_read_b128 v[2:5], v35 offset:0
	ds_read_b128 v[6:9], v36 offset:0
	ds_read_b128 v[10:13], v37 offset:0
	ds_read_b128 v[14:17], v38 offset:0
	ds_read_b128 v[82:85], v74 offset:0
	ds_read_b128 v[86:89], v74 offset:1024
	ds_read_b128 v[90:93], v74 offset:2048
	ds_read_b128 v[94:97], v74 offset:3072
	s_waitcnt lgkmcnt(4)
	v_mfma_f32_32x32x16_bf16 v[18:33], v[2:5], v[130:133], 0
	v_mfma_f32_32x32x16_bf16 v[18:33], v[6:9], v[134:137], v[18:33]
	v_mfma_f32_32x32x16_bf16 v[18:33], v[10:13], v[138:141], v[18:33]
	v_mfma_f32_32x32x16_bf16 v[18:33], v[14:17], v[142:145], v[18:33]
.Lband_s0a:
	s_cmp_lt_i32 s8, 4
	s_cbranch_scc1 .Lband_s0b
	v_fmamk_f32 v53, v51, 0xc3000000, v52
	s_nop 7
	s_nop 4
	v_pk_fma_f32 v[18:19], v[18:19], v[66:67], s[34:35] op_sel_hi:[1,0,1]
	v_pk_fma_f32 v[20:21], v[20:21], v[66:67], s[36:37] op_sel_hi:[1,0,1]
	v_pk_fma_f32 v[22:23], v[22:23], v[66:67], s[38:39] op_sel_hi:[1,0,1]
	v_pk_fma_f32 v[24:25], v[24:25], v[66:67], s[40:41] op_sel_hi:[1,0,1]
	v_pk_fma_f32 v[26:27], v[26:27], v[66:67], s[42:43] op_sel_hi:[1,0,1]
	v_pk_fma_f32 v[28:29], v[28:29], v[66:67], s[44:45] op_sel_hi:[1,0,1]
	v_pk_fma_f32 v[30:31], v[30:31], v[66:67], s[46:47] op_sel_hi:[1,0,1]
	v_pk_fma_f32 v[32:33], v[32:33], v[66:67], s[48:49] op_sel_hi:[1,0,1]
	v_cmp_ge_i32_e64 s[16:17], 0, v55
	v_cmp_ge_i32_e64 s[22:23], 1, v55
	v_cmp_ge_i32_e64 s[24:25], 2, v55
	v_cmp_ge_i32_e64 s[28:29], 3, v55
	v_cmp_ge_i32_e32 vcc, 8, v55
	v_cndmask_b32_e64 v18, v67, v18, s[16:17]
	v_cndmask_b32_e64 v19, v67, v19, s[22:23]
	v_cndmask_b32_e64 v20, v67, v20, s[24:25]
	v_cndmask_b32_e64 v21, v67, v21, s[28:29]
	v_cndmask_b32_e64 v22, v67, v22, vcc
	v_cmp_ge_i32_e64 s[16:17], 9, v55
	v_cmp_ge_i32_e64 s[22:23], 10, v55
	v_cmp_ge_i32_e64 s[24:25], 11, v55
	v_cmp_ge_i32_e64 s[28:29], 16, v55
	v_cmp_ge_i32_e32 vcc, 17, v55
	v_cndmask_b32_e64 v23, v67, v23, s[16:17]
	v_cndmask_b32_e64 v24, v67, v24, s[22:23]
	v_cndmask_b32_e64 v25, v67, v25, s[24:25]
	v_cndmask_b32_e64 v26, v67, v26, s[28:29]
	v_cndmask_b32_e64 v27, v67, v27, vcc
	v_cmp_ge_i32_e64 s[16:17], 18, v55
	v_cmp_ge_i32_e64 s[22:23], 19, v55
	v_cmp_ge_i32_e64 s[24:25], 24, v55
	v_cmp_ge_i32_e64 s[28:29], 25, v55
	v_cmp_ge_i32_e32 vcc, 26, v55
	v_cndmask_b32_e64 v28, v67, v28, s[16:17]
	v_cndmask_b32_e64 v29, v67, v29, s[22:23]
	v_cndmask_b32_e64 v30, v67, v30, s[24:25]
	v_cndmask_b32_e64 v31, v67, v31, s[28:29]
	v_cndmask_b32_e64 v32, v67, v32, vcc
	v_cmp_ge_i32_e64 s[16:17], 27, v55
	s_nop 1
	v_cndmask_b32_e64 v33, v67, v33, s[16:17]
	v_max3_f32 v183, v18, v19, v20
	v_max3_f32 v64, v21, v22, v23
	v_max3_f32 v60, v24, v25, v26
	v_max3_f32 v61, v27, v28, v29
	v_max3_f32 v68, v30, v31, v32
	v_max3_f32 v183, v183, v64, v60
	v_max3_f32 v61, v61, v68, v33
	v_max_f32_e32 v183, v183, v61
	v_add_f32_e32 v183, v183, v53
	v_mov_b32_e32 v64, v183
	s_nop 1
	v_permlane32_swap_b32_e32 v64, v183
	v_max_f32_e32 v183, v183, v64
	v_cmp_lt_f32_e32 vcc, v34, v183
	s_cbranch_vccz .Lband_keep0
	v_max_f32_e32 v64, v49, v183
	v_sub_f32_e32 v60, v49, v64
	v_exp_f32_e32 v60, v60
	v_mov_b32_e32 v49, v64
	v_add_f32_e32 v34, 0x41a00000, v64
	v_mul_f32_e32 v50, v50, v60
	v_pk_mul_f32 v[146:147], v[146:147], v[60:61] op_sel_hi:[1,0]
	v_pk_mul_f32 v[148:149], v[148:149], v[60:61] op_sel_hi:[1,0]
	v_pk_mul_f32 v[150:151], v[150:151], v[60:61] op_sel_hi:[1,0]
	v_pk_mul_f32 v[152:153], v[152:153], v[60:61] op_sel_hi:[1,0]
	v_pk_mul_f32 v[154:155], v[154:155], v[60:61] op_sel_hi:[1,0]
	v_pk_mul_f32 v[156:157], v[156:157], v[60:61] op_sel_hi:[1,0]
	v_pk_mul_f32 v[158:159], v[158:159], v[60:61] op_sel_hi:[1,0]
	v_pk_mul_f32 v[160:161], v[160:161], v[60:61] op_sel_hi:[1,0]
	v_pk_mul_f32 v[184:185], v[184:185], v[60:61] op_sel_hi:[1,0]
	v_pk_mul_f32 v[186:187], v[186:187], v[60:61] op_sel_hi:[1,0]
	v_pk_mul_f32 v[188:189], v[188:189], v[60:61] op_sel_hi:[1,0]
	v_pk_mul_f32 v[190:191], v[190:191], v[60:61] op_sel_hi:[1,0]
	v_pk_mul_f32 v[192:193], v[192:193], v[60:61] op_sel_hi:[1,0]
	v_pk_mul_f32 v[194:195], v[194:195], v[60:61] op_sel_hi:[1,0]
	v_pk_mul_f32 v[196:197], v[196:197], v[60:61] op_sel_hi:[1,0]
	v_pk_mul_f32 v[198:199], v[198:199], v[60:61] op_sel_hi:[1,0]
.Lband_keep0:
	v_sub_f32_e32 v68, v53, v49
	v_pk_add_f32 v[18:19], v[18:19], v[68:69] op_sel_hi:[1,0]
	v_exp_f32_e32 v18, v18
	v_exp_f32_e32 v19, v19
	v_pk_add_f32 v[20:21], v[20:21], v[68:69] op_sel_hi:[1,0]
	v_exp_f32_e32 v20, v20
	v_exp_f32_e32 v21, v21
	v_pk_add_f32 v[22:23], v[22:23], v[68:69] op_sel_hi:[1,0]
	v_exp_f32_e32 v22, v22
	v_exp_f32_e32 v23, v23
	v_pk_add_f32 v[24:25], v[24:25], v[68:69] op_sel_hi:[1,0]
	v_exp_f32_e32 v24, v24
	v_exp_f32_e32 v25, v25
	v_pk_add_f32 v[26:27], v[26:27], v[68:69] op_sel_hi:[1,0]
	v_exp_f32_e32 v26, v26
	v_exp_f32_e32 v27, v27
	v_pk_add_f32 v[28:29], v[28:29], v[68:69] op_sel_hi:[1,0]
	v_exp_f32_e32 v28, v28
	v_exp_f32_e32 v29, v29
	v_pk_add_f32 v[30:31], v[30:31], v[68:69] op_sel_hi:[1,0]
	v_exp_f32_e32 v30, v30
	v_exp_f32_e32 v31, v31
	v_pk_add_f32 v[32:33], v[32:33], v[68:69] op_sel_hi:[1,0]
	v_exp_f32_e32 v32, v32
	v_exp_f32_e32 v33, v33
	v_pk_add_f32 v[68:69], v[18:19], v[20:21]
	v_pk_add_f32 v[60:61], v[22:23], v[24:25]
	v_pk_add_f32 v[68:69], v[68:69], v[26:27]
	v_pk_add_f32 v[60:61], v[60:61], v[28:29]
	v_pk_add_f32 v[68:69], v[68:69], v[30:31]
	v_pk_add_f32 v[60:61], v[60:61], v[32:33]
	v_pk_add_f32 v[68:69], v[68:69], v[60:61]
	v_add_f32_e32 v183, v68, v69
	v_add_f32_e32 v50, v50, v183
	v_cvt_pk_bf16_f32 v18, v18, v19
	v_cvt_pk_bf16_f32 v19, v20, v21
	v_cvt_pk_bf16_f32 v20, v22, v23
	v_cvt_pk_bf16_f32 v21, v24, v25
	v_cvt_pk_bf16_f32 v22, v26, v27
	v_cvt_pk_bf16_f32 v23, v28, v29
	v_cvt_pk_bf16_f32 v24, v30, v31
	v_cvt_pk_bf16_f32 v25, v32, v33
	s_waitcnt lgkmcnt(0)
	s_nop 1
	v_mfma_f32_32x32x16_bf16 v[146:161], v[82:85], v[18:21], v[146:161]
	v_mfma_f32_32x32x16_bf16 v[184:199], v[90:93], v[18:21], v[184:199]
	v_mfma_f32_32x32x16_bf16 v[146:161], v[86:89], v[22:25], v[146:161]
	v_mfma_f32_32x32x16_bf16 v[184:199], v[94:97], v[22:25], v[184:199]
.Lband_s0b:
	s_cmp_lt_i32 s8, 3
	s_cbranch_scc1 .Lband_s1a
	ds_read_b128 v[2:5], v35 offset:4096
	ds_read_b128 v[6:9], v36 offset:4096
	ds_read_b128 v[10:13], v37 offset:4096
	ds_read_b128 v[14:17], v38 offset:4096
	ds_read_b128 v[82:85], v74 offset:4096
	ds_read_b128 v[86:89], v74 offset:5120
	ds_read_b128 v[90:93], v74 offset:6144
	ds_read_b128 v[94:97], v74 offset:7168
	s_waitcnt lgkmcnt(4)
	v_mfma_f32_32x32x16_bf16 v[18:33], v[2:5], v[130:133], 0
	v_mfma_f32_32x32x16_bf16 v[18:33], v[6:9], v[134:137], v[18:33]
	v_mfma_f32_32x32x16_bf16 v[18:33], v[10:13], v[138:141], v[18:33]
	v_mfma_f32_32x32x16_bf16 v[18:33], v[14:17], v[142:145], v[18:33]
.Lband_s1a:
	s_cmp_lt_i32 s8, 3
	s_cbranch_scc1 .Lband_s1b
	v_fmamk_f32 v53, v51, 0xc2c00000, v52
	s_nop 7
	s_nop 4
	v_pk_fma_f32 v[18:19], v[18:19], v[66:67], s[34:35] op_sel_hi:[1,0,1]
	v_pk_fma_f32 v[20:21], v[20:21], v[66:67], s[36:37] op_sel_hi:[1,0,1]
	v_pk_fma_f32 v[22:23], v[22:23], v[66:67], s[38:39] op_sel_hi:[1,0,1]
	v_pk_fma_f32 v[24:25], v[24:25], v[66:67], s[40:41] op_sel_hi:[1,0,1]
	v_pk_fma_f32 v[26:27], v[26:27], v[66:67], s[42:43] op_sel_hi:[1,0,1]
	v_pk_fma_f32 v[28:29], v[28:29], v[66:67], s[44:45] op_sel_hi:[1,0,1]
	v_pk_fma_f32 v[30:31], v[30:31], v[66:67], s[46:47] op_sel_hi:[1,0,1]
	v_pk_fma_f32 v[32:33], v[32:33], v[66:67], s[48:49] op_sel_hi:[1,0,1]
	v_max3_f32 v183, v18, v19, v20
	v_max3_f32 v64, v21, v22, v23
	v_max3_f32 v60, v24, v25, v26
	v_max3_f32 v61, v27, v28, v29
	v_max3_f32 v68, v30, v31, v32
	v_max3_f32 v183, v183, v64, v60
	v_max3_f32 v61, v61, v68, v33
	v_max_f32_e32 v183, v183, v61
	v_add_f32_e32 v183, v183, v53
	v_mov_b32_e32 v64, v183
	s_nop 1
	v_permlane32_swap_b32_e32 v64, v183
	v_max_f32_e32 v183, v183, v64
	v_cmp_lt_f32_e32 vcc, v34, v183
	s_cbranch_vccz .Lband_keep1
	v_max_f32_e32 v64, v49, v183
	v_sub_f32_e32 v60, v49, v64
	v_exp_f32_e32 v60, v60
	v_mov_b32_e32 v49, v64
	v_add_f32_e32 v34, 0x41a00000, v64
	v_mul_f32_e32 v50, v50, v60
	v_pk_mul_f32 v[146:147], v[146:147], v[60:61] op_sel_hi:[1,0]
	v_pk_mul_f32 v[148:149], v[148:149], v[60:61] op_sel_hi:[1,0]
	v_pk_mul_f32 v[150:151], v[150:151], v[60:61] op_sel_hi:[1,0]
	v_pk_mul_f32 v[152:153], v[152:153], v[60:61] op_sel_hi:[1,0]
	v_pk_mul_f32 v[154:155], v[154:155], v[60:61] op_sel_hi:[1,0]
	v_pk_mul_f32 v[156:157], v[156:157], v[60:61] op_sel_hi:[1,0]
	v_pk_mul_f32 v[158:159], v[158:159], v[60:61] op_sel_hi:[1,0]
	v_pk_mul_f32 v[160:161], v[160:161], v[60:61] op_sel_hi:[1,0]
	v_pk_mul_f32 v[184:185], v[184:185], v[60:61] op_sel_hi:[1,0]
	v_pk_mul_f32 v[186:187], v[186:187], v[60:61] op_sel_hi:[1,0]
	v_pk_mul_f32 v[188:189], v[188:189], v[60:61] op_sel_hi:[1,0]
	v_pk_mul_f32 v[190:191], v[190:191], v[60:61] op_sel_hi:[1,0]
	v_pk_mul_f32 v[192:193], v[192:193], v[60:61] op_sel_hi:[1,0]
	v_pk_mul_f32 v[194:195], v[194:195], v[60:61] op_sel_hi:[1,0]
	v_pk_mul_f32 v[196:197], v[196:197], v[60:61] op_sel_hi:[1,0]
	v_pk_mul_f32 v[198:199], v[198:199], v[60:61] op_sel_hi:[1,0]

.Lband_s1b:
	s_cmp_lt_i32 s8, 2
	s_cbranch_scc1 .Lband_s2a
	ds_read_b128 v[2:5], v35 offset:8192
	ds_read_b128 v[6:9], v36 offset:8192
	ds_read_b128 v[10:13], v37 offset:8192
	ds_read_b128 v[14:17], v38 offset:8192
	ds_read_b128 v[82:85], v74 offset:8192
	ds_read_b128 v[86:89], v74 offset:9216
	ds_read_b128 v[90:93], v74 offset:10240
	ds_read_b128 v[94:97], v74 offset:11264
	s_waitcnt lgkmcnt(4)
	v_mfma_f32_32x32x16_bf16 v[18:33], v[2:5], v[130:133], 0
	v_mfma_f32_32x32x16_bf16 v[18:33], v[6:9], v[134:137], v[18:33]
	v_mfma_f32_32x32x16_bf16 v[18:33], v[10:13], v[138:141], v[18:33]
	v_mfma_f32_32x32x16_bf16 v[18:33], v[14:17], v[142:145], v[18:33]

.Lband_s2b:
	s_cmp_lt_i32 s8, 1
	s_cbranch_scc1 .Lband_s3a
	ds_read_b128 v[2:5], v35 offset:12288
	ds_read_b128 v[6:9], v36 offset:12288
	ds_read_b128 v[10:13], v37 offset:12288
	ds_read_b128 v[14:17], v38 offset:12288
	ds_read_b128 v[82:85], v74 offset:12288
	ds_read_b128 v[86:89], v74 offset:13312
	ds_read_b128 v[90:93], v74 offset:14336
	ds_read_b128 v[94:97], v74 offset:15360
	s_waitcnt lgkmcnt(4)
	v_mfma_f32_32x32x16_bf16 v[18:33], v[2:5], v[130:133], 0
	v_mfma_f32_32x32x16_bf16 v[18:33], v[6:9], v[134:137], v[18:33]
	v_mfma_f32_32x32x16_bf16 v[18:33], v[10:13], v[138:141], v[18:33]
	v_mfma_f32_32x32x16_bf16 v[18:33], v[14:17], v[142:145], v[18:33]

.Lband_s3b:
	ds_read_b128 v[2:5], v35 offset:16384
	ds_read_b128 v[6:9], v36 offset:16384
	ds_read_b128 v[10:13], v37 offset:16384
	ds_read_b128 v[14:17], v38 offset:16384
	ds_read_b128 v[82:85], v74 offset:16384
	ds_read_b128 v[86:89], v74 offset:17408
	ds_read_b128 v[90:93], v74 offset:18432
	ds_read_b128 v[94:97], v74 offset:19456
	s_waitcnt lgkmcnt(4)
	v_mfma_f32_32x32x16_bf16 v[18:33], v[2:5], v[130:133], 0
	v_mfma_f32_32x32x16_bf16 v[18:33], v[6:9], v[134:137], v[18:33]
	v_mfma_f32_32x32x16_bf16 v[18:33], v[10:13], v[138:141], v[18:33]
	v_mfma_f32_32x32x16_bf16 v[18:33], v[14:17], v[142:145], v[18:33]
	v_mov_b32_e32 v53, v52
	s_nop 7
	s_nop 4
	v_pk_fma_f32 v[18:19], v[18:19], v[66:67], s[34:35] op_sel_hi:[1,0,1]
	v_pk_fma_f32 v[20:21], v[20:21], v[66:67], s[36:37] op_sel_hi:[1,0,1]
	v_pk_fma_f32 v[22:23], v[22:23], v[66:67], s[38:39] op_sel_hi:[1,0,1]
	v_pk_fma_f32 v[24:25], v[24:25], v[66:67], s[40:41] op_sel_hi:[1,0,1]
	v_pk_fma_f32 v[26:27], v[26:27], v[66:67], s[42:43] op_sel_hi:[1,0,1]
	v_pk_fma_f32 v[28:29], v[28:29], v[66:67], s[44:45] op_sel_hi:[1,0,1]
	v_pk_fma_f32 v[30:31], v[30:31], v[66:67], s[46:47] op_sel_hi:[1,0,1]
	v_pk_fma_f32 v[32:33], v[32:33], v[66:67], s[48:49] op_sel_hi:[1,0,1]
	v_cmp_le_i32_e64 s[16:17], 0, v54
	v_cmp_le_i32_e64 s[22:23], 1, v54
	v_cmp_le_i32_e64 s[24:25], 2, v54
	v_cmp_le_i32_e64 s[28:29], 3, v54
	v_cmp_le_i32_e32 vcc, 8, v54
	v_cndmask_b32_e64 v18, v67, v18, s[16:17]
	v_cndmask_b32_e64 v19, v67, v19, s[22:23]
	v_cndmask_b32_e64 v20, v67, v20, s[24:25]
	v_cndmask_b32_e64 v21, v67, v21, s[28:29]
	v_cndmask_b32_e64 v22, v67, v22, vcc
	v_cmp_le_i32_e64 s[16:17], 9, v54
	v_cmp_le_i32_e64 s[22:23], 10, v54
	v_cmp_le_i32_e64 s[24:25], 11, v54
	v_cmp_le_i32_e64 s[28:29], 16, v54
	v_cmp_le_i32_e32 vcc, 17, v54
	v_cndmask_b32_e64 v23, v67, v23, s[16:17]
	v_cndmask_b32_e64 v24, v67, v24, s[22:23]
	v_cndmask_b32_e64 v25, v67, v25, s[24:25]
	v_cndmask_b32_e64 v26, v67, v26, s[28:29]
	v_cndmask_b32_e64 v27, v67, v27, vcc
	v_cmp_le_i32_e64 s[16:17], 18, v54
	v_cmp_le_i32_e64 s[22:23], 19, v54
	v_cmp_le_i32_e64 s[24:25], 24, v54
	v_cmp_le_i32_e64 s[28:29], 25, v54
	v_cmp_le_i32_e32 vcc, 26, v54
	v_cndmask_b32_e64 v28, v67, v28, s[16:17]
	v_cndmask_b32_e64 v29, v67, v29, s[22:23]
	v_cndmask_b32_e64 v30, v67, v30, s[24:25]
	v_cndmask_b32_e64 v31, v67, v31, s[28:29]
	v_cndmask_b32_e64 v32, v67, v32, vcc
	v_cmp_le_i32_e64 s[16:17], 27, v54
	s_nop 1
	v_cndmask_b32_e64 v33, v67, v33, s[16:17]
	v_max3_f32 v183, v18, v19, v20
	v_max3_f32 v64, v21, v22, v23
	v_max3_f32 v60, v24, v25, v26
	v_max3_f32 v61, v27, v28, v29
	v_max3_f32 v68, v30, v31, v32
	v_max3_f32 v183, v183, v64, v60
	v_max3_f32 v61, v61, v68, v33
	v_max_f32_e32 v183, v183, v61
	v_add_f32_e32 v183, v183, v53
	v_mov_b32_e32 v64, v183
	s_nop 1
	v_permlane32_swap_b32_e32 v64, v183
	v_max_f32_e32 v183, v183, v64
	v_cmp_lt_f32_e32 vcc, v34, v183
	s_cbranch_vccz .Lband_keep4
	v_max_f32_e32 v64, v49, v183
	v_sub_f32_e32 v60, v49, v64
	v_exp_f32_e32 v60, v60
	v_mov_b32_e32 v49, v64
	v_add_f32_e32 v34, 0x41a00000, v64
	v_mul_f32_e32 v50, v50, v60
	v_pk_mul_f32 v[146:147], v[146:147], v[60:61] op_sel_hi:[1,0]
	v_pk_mul_f32 v[148:149], v[148:149], v[60:61] op_sel_hi:[1,0]
	v_pk_mul_f32 v[150:151], v[150:151], v[60:61] op_sel_hi:[1,0]
	v_pk_mul_f32 v[152:153], v[152:153], v[60:61] op_sel_hi:[1,0]
	v_pk_mul_f32 v[154:155], v[154:155], v[60:61] op_sel_hi:[1,0]
	v_pk_mul_f32 v[156:157], v[156:157], v[60:61] op_sel_hi:[1,0]
	v_pk_mul_f32 v[158:159], v[158:159], v[60:61] op_sel_hi:[1,0]
	v_pk_mul_f32 v[160:161], v[160:161], v[60:61] op_sel_hi:[1,0]
	v_pk_mul_f32 v[184:185], v[184:185], v[60:61] op_sel_hi:[1,0]
	v_pk_mul_f32 v[186:187], v[186:187], v[60:61] op_sel_hi:[1,0]
	v_pk_mul_f32 v[188:189], v[188:189], v[60:61] op_sel_hi:[1,0]
	v_pk_mul_f32 v[190:191], v[190:191], v[60:61] op_sel_hi:[1,0]
	v_pk_mul_f32 v[192:193], v[192:193], v[60:61] op_sel_hi:[1,0]
	v_pk_mul_f32 v[194:195], v[194:195], v[60:61] op_sel_hi:[1,0]
	v_pk_mul_f32 v[196:197], v[196:197], v[60:61] op_sel_hi:[1,0]
	v_pk_mul_f32 v[198:199], v[198:199], v[60:61] op_sel_hi:[1,0]
.Lband_keep4:
	v_sub_f32_e32 v68, v53, v49
	v_pk_add_f32 v[18:19], v[18:19], v[68:69] op_sel_hi:[1,0]
	v_exp_f32_e32 v18, v18
	v_exp_f32_e32 v19, v19
	v_pk_add_f32 v[20:21], v[20:21], v[68:69] op_sel_hi:[1,0]
	v_exp_f32_e32 v20, v20
	v_exp_f32_e32 v21, v21
	v_pk_add_f32 v[22:23], v[22:23], v[68:69] op_sel_hi:[1,0]
	v_exp_f32_e32 v22, v22
	v_exp_f32_e32 v23, v23
	v_pk_add_f32 v[24:25], v[24:25], v[68:69] op_sel_hi:[1,0]
	v_exp_f32_e32 v24, v24
	v_exp_f32_e32 v25, v25
	v_pk_add_f32 v[26:27], v[26:27], v[68:69] op_sel_hi:[1,0]
	v_exp_f32_e32 v26, v26
	v_exp_f32_e32 v27, v27
	v_pk_add_f32 v[28:29], v[28:29], v[68:69] op_sel_hi:[1,0]
	v_exp_f32_e32 v28, v28
	v_exp_f32_e32 v29, v29
	v_pk_add_f32 v[30:31], v[30:31], v[68:69] op_sel_hi:[1,0]
	v_exp_f32_e32 v30, v30
	v_exp_f32_e32 v31, v31
	v_pk_add_f32 v[32:33], v[32:33], v[68:69] op_sel_hi:[1,0]
	v_exp_f32_e32 v32, v32
	v_exp_f32_e32 v33, v33
	v_pk_add_f32 v[68:69], v[18:19], v[20:21]
	v_pk_add_f32 v[60:61], v[22:23], v[24:25]
	v_pk_add_f32 v[68:69], v[68:69], v[26:27]
	v_pk_add_f32 v[60:61], v[60:61], v[28:29]
	v_pk_add_f32 v[68:69], v[68:69], v[30:31]
	v_pk_add_f32 v[60:61], v[60:61], v[32:33]
	v_pk_add_f32 v[68:69], v[68:69], v[60:61]
	v_add_f32_e32 v183, v68, v69
	v_add_f32_e32 v50, v50, v183
	v_cvt_pk_bf16_f32 v18, v18, v19
	v_cvt_pk_bf16_f32 v19, v20, v21
	v_cvt_pk_bf16_f32 v20, v22, v23
	v_cvt_pk_bf16_f32 v21, v24, v25
	v_cvt_pk_bf16_f32 v22, v26, v27
	v_cvt_pk_bf16_f32 v23, v28, v29
	v_cvt_pk_bf16_f32 v24, v30, v31
	v_cvt_pk_bf16_f32 v25, v32, v33
	s_waitcnt lgkmcnt(0)
	s_nop 1
	v_mfma_f32_32x32x16_bf16 v[146:161], v[82:85], v[18:21], v[146:161]
	v_mfma_f32_32x32x16_bf16 v[184:199], v[90:93], v[18:21], v[184:199]
	v_mfma_f32_32x32x16_bf16 v[146:161], v[86:89], v[22:25], v[146:161]
	v_mfma_f32_32x32x16_bf16 v[184:199], v[94:97], v[22:25], v[184:199]
	s_nop 7
	s_nop 7
	v_mov_b32_e32 v64, v50
	s_nop 1
	v_permlane32_swap_b32_e32 v64, v50
	v_add_f32_e32 v50, v50, v64
	v_log_f32_e32 v183, v50
	v_rcp_f32_e32 v64, v50
	s_nop 0
	v_fma_f32 v60, -v50, v64, 1.0
	v_fma_f32 v64, v64, v60, v64
	v_add_f32_e32 v183, v49, v183
	v_mul_f32_e32 v183, 0x3f317218, v183
	s_cmp_eq_u32 s1, 0
	s_cbranch_scc1 .Lband_epi_swa
	v_mov_b32_e32 v60, v64
	v_cmp_eq_u32_e32 vcc, 0, v48
	s_and_saveexec_b64 s[16:17], vcc
	global_store_dword v63, v183, s[26:27]
	s_or_b64 exec, exec, s[16:17]
	s_branch .Lband_epi_scale

.Lband_epi_scale:
	v_pk_mul_f32 v[146:147], v[146:147], v[60:61] op_sel_hi:[1,0]
	v_pk_mul_f32 v[148:149], v[148:149], v[60:61] op_sel_hi:[1,0]
	v_pk_mul_f32 v[150:151], v[150:151], v[60:61] op_sel_hi:[1,0]
	v_pk_mul_f32 v[152:153], v[152:153], v[60:61] op_sel_hi:[1,0]
	v_pk_mul_f32 v[154:155], v[154:155], v[60:61] op_sel_hi:[1,0]
	v_pk_mul_f32 v[156:157], v[156:157], v[60:61] op_sel_hi:[1,0]
	v_pk_mul_f32 v[158:159], v[158:159], v[60:61] op_sel_hi:[1,0]
	v_pk_mul_f32 v[160:161], v[160:161], v[60:61] op_sel_hi:[1,0]
	v_pk_mul_f32 v[184:185], v[184:185], v[60:61] op_sel_hi:[1,0]
	v_pk_mul_f32 v[186:187], v[186:187], v[60:61] op_sel_hi:[1,0]
	v_pk_mul_f32 v[188:189], v[188:189], v[60:61] op_sel_hi:[1,0]
	v_pk_mul_f32 v[190:191], v[190:191], v[60:61] op_sel_hi:[1,0]
	v_pk_mul_f32 v[192:193], v[192:193], v[60:61] op_sel_hi:[1,0]
	v_pk_mul_f32 v[194:195], v[194:195], v[60:61] op_sel_hi:[1,0]
	v_pk_mul_f32 v[196:197], v[196:197], v[60:61] op_sel_hi:[1,0]
	v_pk_mul_f32 v[198:199], v[198:199], v[60:61] op_sel_hi:[1,0]
	v_cvt_pk_bf16_f32 v146, v146, v147
	v_cvt_pk_bf16_f32 v147, v148, v149
	global_store_dwordx2 v62, v[146:147], s[6:7]
	v_cvt_pk_bf16_f32 v150, v150, v151
	v_cvt_pk_bf16_f32 v151, v152, v153
	global_store_dwordx2 v62, v[150:151], s[6:7] offset:16
	v_cvt_pk_bf16_f32 v154, v154, v155
	v_cvt_pk_bf16_f32 v155, v156, v157
	global_store_dwordx2 v62, v[154:155], s[6:7] offset:32
	v_cvt_pk_bf16_f32 v158, v158, v159
	v_cvt_pk_bf16_f32 v159, v160, v161
	global_store_dwordx2 v62, v[158:159], s[6:7] offset:48
	v_cvt_pk_bf16_f32 v184, v184, v185
	v_cvt_pk_bf16_f32 v185, v186, v187
	global_store_dwordx2 v62, v[184:185], s[6:7] offset:64
	v_cvt_pk_bf16_f32 v188, v188, v189
	v_cvt_pk_bf16_f32 v189, v190, v191
	global_store_dwordx2 v62, v[188:189], s[6:7] offset:80
	v_cvt_pk_bf16_f32 v192, v192, v193
	v_cvt_pk_bf16_f32 v193, v194, v195
	global_store_dwordx2 v62, v[192:193], s[6:7] offset:96
	v_cvt_pk_bf16_f32 v196, v196, v197
	v_cvt_pk_bf16_f32 v197, v198, v199
	global_store_dwordx2 v62, v[196:197], s[6:7] offset:112
	s_add_i32 s0, s0, s68
	s_cmp_lt_u32 s0, 0x4000
	s_cbranch_scc1 .Lband_item
	v_lshlrev_b32_e32 v183, 2, v220
	v_add_u32_e32 v2, 0x10000, v183
	v_lshrrev_b32_e32 v183, 6, v220
	v_lshlrev_b32_e32 v183, 8, v183
	v_add_u32_e32 v183, 0x0, v183
	ds_read_b32 v2, v183 offset:0
	ds_read_b32 v3, v183 offset:4
	ds_read_b32 v4, v183 offset:8
	ds_read_b32 v5, v183 offset:12
	ds_read_b32 v6, v183 offset:16
	ds_read_b32 v7, v183 offset:20
	ds_read_b32 v8, v183 offset:24
	ds_read_b32 v9, v183 offset:28
	ds_read_b32 v10, v183 offset:32
	ds_read_b32 v11, v183 offset:36
	ds_read_b32 v12, v183 offset:40
	ds_read_b32 v13, v183 offset:44
	ds_read_b32 v14, v183 offset:48
	ds_read_b32 v15, v183 offset:52
	ds_read_b32 v16, v183 offset:56
	ds_read_b32 v17, v183 offset:60
	ds_read_b32 v18, v183 offset:64
	ds_read_b32 v19, v183 offset:68
	ds_read_b32 v20, v183 offset:72
	ds_read_b32 v21, v183 offset:76
	ds_read_b32 v22, v183 offset:80
	ds_read_b32 v23, v183 offset:84
	ds_read_b32 v24, v183 offset:88
	ds_read_b32 v25, v183 offset:92
	ds_read_b32 v26, v183 offset:96
	ds_read_b32 v27, v183 offset:100
	ds_read_b32 v28, v183 offset:104
	ds_read_b32 v29, v183 offset:108
	ds_read_b32 v30, v183 offset:112
	ds_read_b32 v31, v183 offset:116
	ds_read_b32 v32, v183 offset:120
	ds_read_b32 v33, v183 offset:124
	ds_read_b32 v34, v183 offset:128
	ds_read_b32 v35, v183 offset:132
	ds_read_b32 v36, v183 offset:136
	ds_read_b32 v37, v183 offset:140
	ds_read_b32 v38, v183 offset:144
	ds_read_b32 v39, v183 offset:148
	ds_read_b32 v40, v183 offset:152
	ds_read_b32 v41, v183 offset:156
	ds_read_b32 v42, v183 offset:160
	ds_read_b32 v43, v183 offset:164
	ds_read_b32 v44, v183 offset:168
	ds_read_b32 v45, v183 offset:172
	ds_read_b32 v46, v183 offset:176
	ds_read_b32 v47, v183 offset:180
	ds_read_b32 v48, v183 offset:184
	ds_read_b32 v49, v183 offset:188
	ds_read_b32 v50, v183 offset:192
	ds_read_b32 v51, v183 offset:196
	ds_read_b32 v52, v183 offset:200
	ds_read_b32 v53, v183 offset:204
	ds_read_b32 v54, v183 offset:208
	s_waitcnt lgkmcnt(0)
	v_readfirstlane_b32 s52, v54
	s_nop 3
	s_mov_b32 m0, s52
	v_readfirstlane_b32 s2, v2
	v_readfirstlane_b32 s3, v3
	v_readfirstlane_b32 s4, v4
	v_readfirstlane_b32 s5, v5
	v_readfirstlane_b32 s6, v6
	v_readfirstlane_b32 s7, v7
	v_readfirstlane_b32 s8, v8
	v_readfirstlane_b32 s9, v9
	v_readfirstlane_b32 s10, v10
	v_readfirstlane_b32 s11, v11
	v_readfirstlane_b32 s12, v12
	v_readfirstlane_b32 s13, v13
	v_readfirstlane_b32 s14, v14
	v_readfirstlane_b32 s15, v15
	v_readfirstlane_b32 s16, v16
	v_readfirstlane_b32 s17, v17
	v_readfirstlane_b32 s18, v18
	v_readfirstlane_b32 s19, v19
	v_readfirstlane_b32 s20, v20
	v_readfirstlane_b32 s21, v21
	v_readfirstlane_b32 s22, v22
	v_readfirstlane_b32 s23, v23
	v_readfirstlane_b32 s24, v24
	v_readfirstlane_b32 s25, v25
	v_readfirstlane_b32 s26, v26
	v_readfirstlane_b32 s27, v27
	v_readfirstlane_b32 s28, v28
	v_readfirstlane_b32 s29, v29
	v_readfirstlane_b32 s30, v30
	v_readfirstlane_b32 s34, v31
	v_readfirstlane_b32 s35, v32
	v_readfirstlane_b32 s36, v33
	v_readfirstlane_b32 s37, v34
	v_readfirstlane_b32 s38, v35
	v_readfirstlane_b32 s39, v36
	v_readfirstlane_b32 s40, v37
	v_readfirstlane_b32 s41, v38
	v_readfirstlane_b32 s42, v39
	v_readfirstlane_b32 s43, v40
	v_readfirstlane_b32 s44, v41
	v_readfirstlane_b32 s45, v42
	v_readfirstlane_b32 s46, v43
	v_readfirstlane_b32 s47, v44
	v_readfirstlane_b32 s48, v45
	v_readfirstlane_b32 s49, v46
	v_readfirstlane_b32 s50, v47
	v_readfirstlane_b32 s51, v48
	v_readfirstlane_b32 s52, v49
	v_readfirstlane_b32 s53, v50
	v_readfirstlane_b32 s54, v51
	v_readfirstlane_b32 s55, v52
	v_readfirstlane_b32 s56, v53
	s_waitcnt vmcnt(0)
	s_branch .Lband_exit
